# diff-attn plain-tile loop hand-pipelined: QK/PV MFMAs interleaved with softmax VALU, DMA interleaved
# speedup vs baseline: 1.0277x; 1.0277x over previous
.LBB0_459:
	s_or_b64 exec, exec, s[0:1]
	s_lshl_b32 s0, s10, 5
	s_and_b32 s72, s0, 0xffffff00
	s_lshl_b32 s0, s7, 2
	v_mov_b32_e32 v0, s0
	s_lshl_b32 s7, s85, 2
	s_lshl_b32 s0, s6, 1
	s_or_b32 s48, s7, s0
	s_lshl_b64 s[0:1], s[48:49], 2
	s_add_u32 s0, s28, s0
	s_addc_u32 s1, s29, s1
	s_ashr_i32 s73, s72, 31
	v_mov_b32_e32 v2, s7
	global_load_dword v4, v0, s[52:53]
	global_load_dword v5, v0, s[52:53] offset:1024
	s_nop 0
	global_load_dwordx2 v[0:1], v133, s[0:1] offset:256
	global_load_dword v6, v2, s[28:29] offset:512
	s_lshl_b64 s[0:1], s[72:73], 11
	s_add_u32 s0, s20, s0
	s_addc_u32 s1, s21, s1
	s_lshl_b32 s7, s85, 8
	s_add_u32 s0, s0, s7
	s_addc_u32 s1, s1, 0
	s_lshl_b32 s8, s6, 7
	s_add_u32 s0, s0, s8
	s_addc_u32 s1, s1, 0
	s_add_u32 s9, s3, s7
	s_addc_u32 s11, s55, 0
	s_add_u32 s12, s9, s8
	s_addc_u32 s13, s11, 0
	v_mov_b32_e32 v7, v205
	s_add_u32 s16, s69, s7
	s_addc_u32 s11, s74, 0
	v_readfirstlane_b32 s17, v7
	s_ashr_i32 s9, s17, 6
	v_and_b32_e32 v213, 31, v7
	s_lshl_b32 s87, s9, 5
	v_or_b32_e32 v2, s87, v213
	v_ashrrev_i32_e32 v3, 31, v2
	v_bfe_u32 v212, v7, 5, 1
	v_lshlrev_b64 v[2:3], 11, v[2:3]
	v_lshl_add_u64 v[2:3], s[0:1], 0, v[2:3]
	v_lshlrev_b32_e32 v132, 4, v212
	v_lshl_add_u64 v[2:3], v[2:3], 0, v[132:133]
	global_load_dwordx4 v[114:117], v[2:3], off
	global_load_dwordx4 v[118:121], v[2:3], off offset:32
	global_load_dwordx4 v[122:125], v[2:3], off offset:64
	global_load_dwordx4 v[126:129], v[2:3], off offset:96
	v_mov_b32_e32 v8, s17
	s_ashr_i32 s0, s17, 31
	v_bfi_b32 v8, s77, v8, v7
	s_lshr_b32 s0, s0, 29
	v_add_u32_e32 v9, s0, v8
	v_ashrrev_i32_e32 v10, 3, v9
	v_lshrrev_b32_e32 v11, 1, v10
	v_bfe_u32 v12, v10, 1, 1
	v_lshrrev_b32_e32 v13, 2, v10
	v_and_b32_e32 v14, 0x1ffff3, v10
	s_and_b32 s8, s17, 0xffffffc0
	v_and_b32_e32 v9, 0xffffff8, v9
	v_and_b32_e32 v13, 6, v13
	s_and_b32 s13, s13, 0xffff
	s_mov_b32 s18, s14
	s_mov_b32 s19, s15
	v_and_b32_e32 v217, 63, v7
	s_mov_b32 s7, 0
	v_lshl_add_u32 v219, v213, 7, 0
	s_waitcnt vmcnt(7)
	v_readfirstlane_b32 s60, v4
	s_waitcnt vmcnt(6)
	v_readfirstlane_b32 s84, v5
	s_waitcnt vmcnt(5)
	v_add_f32_e32 v0, v0, v1
	s_waitcnt vmcnt(3)
	v_lshlrev_b32_e32 v15, 16, v116
	v_readfirstlane_b32 s0, v0
	s_waitcnt vmcnt(2)
	v_lshlrev_b32_e32 v19, 16, v118
	v_and_b32_e32 v20, 0xffff0000, v118
	v_mul_f32_e32 v0, s0, v208
	v_mov_b32_e32 v1, s0
	v_cmp_lt_f32_e32 vcc, s0, v207
	v_fma_f32 v19, v19, v19, 0
	v_lshlrev_b32_e32 v21, 16, v119
	v_cndmask_b32_e32 v0, v1, v0, vcc
	v_sqrt_f32_e32 v1, v0
	v_fmac_f32_e32 v19, v20, v20
	v_and_b32_e32 v22, 0xffff0000, v119
	v_fmac_f32_e32 v19, v21, v21
	v_add_u32_e32 v2, -1, v1
	v_add_u32_e32 v3, 1, v1
	v_fma_f32 v4, -v2, v1, v0
	v_fma_f32 v5, -v3, v1, v0
	v_cmp_ge_f32_e64 s[0:1], 0, v4
	v_lshlrev_b32_e32 v4, 16, v115
	v_lshlrev_b32_e32 v23, 16, v120
	v_cndmask_b32_e64 v1, v1, v2, s[0:1]
	v_cmp_lt_f32_e64 s[0:1], 0, v5
	v_and_b32_e32 v5, 0xffff0000, v115
	v_fmac_f32_e32 v19, v22, v22
	v_cndmask_b32_e64 v1, v1, v3, s[0:1]
	v_mul_f32_e32 v2, 0x37800000, v1
	v_cndmask_b32_e32 v1, v1, v2, vcc
	v_lshlrev_b32_e32 v2, 16, v114
	v_and_b32_e32 v3, 0xffff0000, v114
	v_fma_f32 v2, v2, v2, 0
	v_fmac_f32_e32 v2, v3, v3
	v_fmac_f32_e32 v2, v4, v4
	v_fmac_f32_e32 v2, v5, v5
	v_lshlrev_b32_e32 v3, 1, v10
	v_bfe_u32 v5, v7, 2, 2
	v_lshrrev_b32_e32 v10, 1, v7
	v_and_b32_e32 v3, 8, v3
	v_and_b32_e32 v4, 4, v11
	v_and_or_b32 v5, v10, 8, v5
	v_lshlrev_b32_e32 v10, 3, v7
	v_or3_b32 v3, v14, v3, v4
	v_and_b32_e32 v4, 32, v7
	s_and_b32 s0, s17, 64
	v_and_b32_e32 v10, 24, v10
	v_or3_b32 v4, s0, v4, v10
	s_ashr_i32 s0, s8, 4
	s_and_b32 s1, s0, 0x1ffff0
	s_lshr_b32 s0, s0, 1
	s_and_b32 s0, s0, 4
	s_or_b32 s0, s1, s0
	v_or_b32_e32 v10, s0, v5
	s_add_i32 s0, s8, 0x200
	s_ashr_i32 s0, s0, 4
	s_and_b32 s1, s0, 0x1ffff0
	s_lshr_b32 s0, s0, 1
	s_and_b32 s0, s0, 4
	s_or_b32 s0, s1, s0
	v_lshlrev_b32_e32 v4, 1, v4
	v_or_b32_e32 v5, s0, v5
	v_lshl_or_b32 v214, v10, 11, v4
	v_lshl_or_b32 v215, v5, 11, v4
	v_sub_u32_e32 v4, v8, v9
	s_lshl_b32 s0, s9, 10
	v_bitop3_b32 v4, v12, v4, v13 bitop3:0x36
	s_add_i32 s9, s0, 0
	v_lshlrev_b32_e32 v4, 4, v4
	s_add_i32 s48, s9, 0x8000
	v_lshl_add_u32 v216, v3, 11, v4
	s_mov_b32 m0, s48
	s_and_b32 s17, s11, 0xffff
	buffer_load_dwordx4 v216, s[12:15], 0 offen lds
	s_mov_b32 m0, s9
	s_add_i32 s73, s9, 0x2000
	buffer_load_dwordx4 v214, s[16:19], 0 offen lds
	s_mov_b32 m0, s73
	s_waitcnt vmcnt(3)
	v_lshlrev_b32_e32 v3, 16, v122
	buffer_load_dwordx4 v215, s[16:19], 0 offen lds
	v_and_b32_e32 v4, 0xffff0000, v122
	v_fma_f32 v3, v3, v3, 0
	v_fmac_f32_e32 v3, v4, v4
	v_lshlrev_b32_e32 v4, 16, v123
	v_and_b32_e32 v5, 0xffff0000, v123
	v_fmac_f32_e32 v3, v4, v4
	v_and_b32_e32 v16, 0xffff0000, v116
	v_and_b32_e32 v24, 0xffff0000, v120
	v_fmac_f32_e32 v2, v15, v15
	v_fmac_f32_e32 v19, v23, v23
	v_fmac_f32_e32 v3, v5, v5
	v_lshlrev_b32_e32 v4, 16, v124
	v_lshlrev_b32_e32 v17, 16, v117
	v_lshlrev_b32_e32 v25, 16, v121
	v_fmac_f32_e32 v2, v16, v16
	v_fmac_f32_e32 v19, v24, v24
	v_and_b32_e32 v5, 0xffff0000, v124
	v_fmac_f32_e32 v3, v4, v4
	v_and_b32_e32 v18, 0xffff0000, v117
	v_and_b32_e32 v26, 0xffff0000, v121
	v_fmac_f32_e32 v2, v17, v17
	v_fmac_f32_e32 v19, v25, v25
	v_fmac_f32_e32 v3, v5, v5
	v_lshlrev_b32_e32 v4, 16, v125
	v_fmac_f32_e32 v2, v18, v18
	v_fmac_f32_e32 v19, v26, v26
	v_and_b32_e32 v5, 0xffff0000, v125
	v_fmac_f32_e32 v3, v4, v4
	v_add_f32_e32 v2, v2, v19
	v_fmac_f32_e32 v3, v5, v5
	v_add_f32_e32 v2, v2, v3
	s_waitcnt vmcnt(3)
	v_lshlrev_b32_e32 v3, 16, v126
	v_and_b32_e32 v4, 0xffff0000, v126
	v_fma_f32 v3, v3, v3, 0
	v_fmac_f32_e32 v3, v4, v4
	v_lshlrev_b32_e32 v4, 16, v127
	v_and_b32_e32 v5, 0xffff0000, v127
	v_fmac_f32_e32 v3, v4, v4
	v_fmac_f32_e32 v3, v5, v5
	v_lshlrev_b32_e32 v4, 16, v128
	v_and_b32_e32 v5, 0xffff0000, v128
	v_fmac_f32_e32 v3, v4, v4
	v_fmac_f32_e32 v3, v5, v5
	v_lshlrev_b32_e32 v4, 16, v129
	v_and_b32_e32 v5, 0xffff0000, v129
	v_fmac_f32_e32 v3, v4, v4
	v_fmac_f32_e32 v3, v5, v5
	v_add_f32_e32 v2, v2, v3
	v_mov_b32_e32 v3, v2
	s_nop 1
	v_permlane32_swap_b32_e32 v2, v3
	v_add_f32_e32 v2, v2, v3
	v_mul_f32_e32 v3, 0x4f800000, v2
	v_cmp_gt_f32_e32 vcc, s76, v2
	v_cmp_class_f32_e64 s[0:1], v0, v209
	v_readfirstlane_b32 s11, v6
	v_cndmask_b32_e32 v2, v2, v3, vcc
	v_sqrt_f32_e32 v3, v2
	v_cndmask_b32_e64 v0, v1, v0, s[0:1]
	s_waitcnt vmcnt(0)
	s_cmp_lt_i32 s10, 8
	v_add_u32_e32 v1, -1, v3
	v_fma_f32 v4, -v1, v3, v2
	v_cmp_ge_f32_e64 s[0:1], 0, v4
	v_add_u32_e32 v4, 1, v3
	s_waitcnt vmcnt(0) lgkmcnt(0)
	v_cndmask_b32_e64 v1, v3, v1, s[0:1]
	v_fma_f32 v3, -v4, v3, v2
	v_cmp_lt_f32_e64 s[0:1], 0, v3
	s_barrier
	s_nop 0
	v_cndmask_b32_e64 v1, v1, v4, s[0:1]
	v_mul_f32_e32 v3, 0x37800000, v1
	v_cndmask_b32_e32 v1, v1, v3, vcc
	v_cmp_class_f32_e32 vcc, v2, v209
	v_lshlrev_b32_e32 v3, 1, v7
	v_and_b32_e32 v3, 32, v3
	v_cndmask_b32_e32 v1, v1, v2, vcc
	v_lshlrev_b32_e32 v2, 4, v7
	v_fma_f32 v223, v0, v1, s11
	v_lshlrev_b32_e32 v1, 3, v217
	v_and_b32_e32 v2, 0xc0, v2
	v_lshrrev_b32_e32 v0, 2, v7
	v_and_or_b32 v2, v1, 24, v2
	v_and_b32_e32 v1, 0x100, v1
	v_or3_b32 v220, v2, v3, v1
	v_bfe_u32 v1, v7, 1, 1
	v_and_b32_e32 v0, 6, v0
	v_add_u32_e32 v218, 0, v220
	v_or_b32_e32 v221, v1, v0
	v_bitop3_b32 v222, v1, v212, v0 bitop3:0x36
	s_cbranch_scc1 .LBB0_462
	v_sub_f32_e32 v66, s60, v223
	v_mov_b32_e32 v67, v66
	v_mov_b32_e32 v68, v66
	v_mov_b32_e32 v69, v66
	v_mov_b32_e32 v70, v66
	v_mov_b32_e32 v71, v66
	v_mov_b32_e32 v72, v66
	v_mov_b32_e32 v73, v66
	v_mov_b32_e32 v74, v66
	v_mov_b32_e32 v75, v66
	v_mov_b32_e32 v76, v66
	v_mov_b32_e32 v77, v66
	v_mov_b32_e32 v78, v66
	v_mov_b32_e32 v79, v66
	v_mov_b32_e32 v80, v66
	v_mov_b32_e32 v81, v66
	v_mov_b32_e32 v64, 0
	v_mov_b32_e32 v0, 0
	v_mov_b32_e32 v1, 0
	v_mov_b32_e32 v2, 0
	v_mov_b32_e32 v3, 0
	v_mov_b32_e32 v4, 0
	v_mov_b32_e32 v5, 0
	v_mov_b32_e32 v6, 0
	v_mov_b32_e32 v7, 0
	v_mov_b32_e32 v8, 0
	v_mov_b32_e32 v9, 0
	v_mov_b32_e32 v10, 0
	v_mov_b32_e32 v11, 0
	v_mov_b32_e32 v12, 0
	v_mov_b32_e32 v13, 0
	v_mov_b32_e32 v14, 0
	v_mov_b32_e32 v15, 0
	v_mov_b32_e32 v16, 0
	v_mov_b32_e32 v17, 0
	v_mov_b32_e32 v18, 0
	v_mov_b32_e32 v19, 0
	v_mov_b32_e32 v20, 0
	v_mov_b32_e32 v21, 0
	v_mov_b32_e32 v22, 0
	v_mov_b32_e32 v23, 0
	v_mov_b32_e32 v24, 0
	v_mov_b32_e32 v25, 0
	v_mov_b32_e32 v26, 0
	v_mov_b32_e32 v27, 0
	v_mov_b32_e32 v28, 0
	v_mov_b32_e32 v29, 0
	v_mov_b32_e32 v30, 0
	v_mov_b32_e32 v31, 0
	v_mov_b32_e32 v32, 0
	v_mov_b32_e32 v33, 0
	v_mov_b32_e32 v34, 0
	v_mov_b32_e32 v35, 0
	v_mov_b32_e32 v36, 0
	v_mov_b32_e32 v37, 0
	v_mov_b32_e32 v38, 0
	v_mov_b32_e32 v39, 0
	v_mov_b32_e32 v40, 0
	v_mov_b32_e32 v41, 0
	v_mov_b32_e32 v42, 0
	v_mov_b32_e32 v43, 0
	v_mov_b32_e32 v44, 0
	v_mov_b32_e32 v45, 0
	v_mov_b32_e32 v46, 0
	v_mov_b32_e32 v47, 0
	v_mov_b32_e32 v48, 0
	v_mov_b32_e32 v49, 0
	v_mov_b32_e32 v50, 0
	v_mov_b32_e32 v51, 0
	v_mov_b32_e32 v52, 0
	v_mov_b32_e32 v53, 0
	v_mov_b32_e32 v54, 0
	v_mov_b32_e32 v55, 0
	v_mov_b32_e32 v56, 0
	v_mov_b32_e32 v57, 0
	v_mov_b32_e32 v58, 0
	v_mov_b32_e32 v59, 0
	v_mov_b32_e32 v60, 0
	v_mov_b32_e32 v61, 0
	v_mov_b32_e32 v62, 0
	v_mov_b32_e32 v63, 0
	s_add_i32 s0, s72, 0xffffff41
	s_lshr_b32 s0, s0, 6
	s_add_i32 s0, s0, 1
	s_and_b32 s97, s0, -2
	s_mov_b32 s7, 0
	s_mov_b32 s98, 0
	s_branch .Lac_core

.LBB0_468:
	s_cmpk_gt_u32 s7, 0xff
	s_cbranch_scc1 .LBB0_473
	v_sub_f32_e32 v66, s84, v223
	v_mov_b32_e32 v67, v66
	v_mov_b32_e32 v68, v66
	v_mov_b32_e32 v69, v66
	v_mov_b32_e32 v70, v66
	v_mov_b32_e32 v71, v66
	v_mov_b32_e32 v72, v66
	v_mov_b32_e32 v73, v66
	v_mov_b32_e32 v74, v66
	v_mov_b32_e32 v75, v66
	v_mov_b32_e32 v76, v66
	v_mov_b32_e32 v77, v66
	v_mov_b32_e32 v78, v66
	v_mov_b32_e32 v79, v66
	v_mov_b32_e32 v80, v66
	v_mov_b32_e32 v81, v66
	s_movk_i32 s97, 0x100
	s_mov_b32 s98, 1
.Lac_core:
	s_add_i32 s91, s9, 0x8000
	s_add_i32 s92, s9, 0xa000
	s_add_i32 s93, s9, 0x2000
	s_add_i32 s94, s9, 0x4000
	s_add_i32 s95, s9, 0x6000
	s_mov_b32 s18, s14
	s_mov_b32 s19, s15
	s_lshl_b32 s96, s7, 17
	s_add_i32 s96, s96, 0x20000
	s_mov_b32 m0, s92
	s_nop 0
	buffer_load_dwordx4 v216, s[12:15], s96 offen lds
	s_add_i32 s96, s96, 0x20000
	v_lshlrev_b32_e32 v225, 4, v222
	v_bitop3_b32 v226, v212, v221, 2 bitop3:0x36
	v_bitop3_b32 v227, v212, v221, 4 bitop3:0x36
	v_bitop3_b32 v228, v212, v221, 6 bitop3:0x36
	v_lshlrev_b32_e32 v226, 4, v226
	v_lshlrev_b32_e32 v227, 4, v227
	v_lshlrev_b32_e32 v228, 4, v228
	v_add_u32_e32 v225, v219, v225
	v_add_u32_e32 v226, v219, v226
	v_add_u32_e32 v227, v219, v227
	v_add_u32_e32 v228, v219, v228
	ds_read_b128 v[182:185], v225 offset:32768
	ds_read_b128 v[186:189], v226 offset:32768
	ds_read_b128 v[190:193], v227 offset:32768
	ds_read_b128 v[194:197], v228 offset:32768
	s_waitcnt lgkmcnt(3)
	v_mfma_f32_32x32x16_bf16 v[82:97], v[182:185], v[114:117], v[66:81]
	ds_read_b128 v[182:185], v225 offset:36864
	v_mov_b32_e32 v230, 0
	v_mov_b32_e32 v231, 0
	v_mov_b32_e32 v232, 0
	v_mov_b32_e32 v233, 0
	v_mov_b32_e32 v234, 0
	v_mov_b32_e32 v235, 0
	s_waitcnt lgkmcnt(3)
	v_mfma_f32_32x32x16_bf16 v[82:97], v[186:189], v[118:121], v[82:97]
	ds_read_b128 v[186:189], v226 offset:36864
	v_mov_b32_e32 v236, 0
	v_mov_b32_e32 v237, 0
	v_mov_b32_e32 v238, 0
	v_mov_b32_e32 v239, 0
	v_mov_b32_e32 v240, 0
	v_mov_b32_e32 v241, 0
	s_waitcnt lgkmcnt(3)
	v_mfma_f32_32x32x16_bf16 v[82:97], v[190:193], v[122:125], v[82:97]
	ds_read_b128 v[190:193], v227 offset:36864
	v_mov_b32_e32 v242, 0
	v_mov_b32_e32 v243, 0
	v_mov_b32_e32 v244, 0
	v_mov_b32_e32 v245, 0
	v_mov_b32_e32 v158, 0
	v_mov_b32_e32 v159, 0
	s_waitcnt lgkmcnt(3)
	v_mfma_f32_32x32x16_bf16 v[82:97], v[194:197], v[126:129], v[82:97]
	ds_read_b128 v[194:197], v228 offset:36864
	v_mov_b32_e32 v160, 0
	v_mov_b32_e32 v161, 0
	v_mov_b32_e32 v162, 0
	v_mov_b32_e32 v163, 0
	v_mov_b32_e32 v164, 0
	v_mov_b32_e32 v165, 0
	s_waitcnt lgkmcnt(3)
	v_mfma_f32_32x32x16_bf16 v[98:113], v[182:185], v[114:117], v[66:81]
	v_mov_b32_e32 v166, 0
	v_mov_b32_e32 v167, 0
	v_mov_b32_e32 v168, 0
	v_mov_b32_e32 v169, 0
	v_mov_b32_e32 v170, 0
	v_mov_b32_e32 v171, 0
	v_mov_b32_e32 v172, 0
	s_waitcnt lgkmcnt(2)
	v_mfma_f32_32x32x16_bf16 v[98:113], v[186:189], v[118:121], v[98:113]
	v_mov_b32_e32 v173, 0
	v_mov_b32_e32 v65, 0
	s_waitcnt lgkmcnt(1)
	v_mfma_f32_32x32x16_bf16 v[98:113], v[190:193], v[122:125], v[98:113]
	s_waitcnt lgkmcnt(0)
	v_mfma_f32_32x32x16_bf16 v[98:113], v[194:197], v[126:129], v[98:113]
	v_mov_b32_e32 v182, 0
	v_mov_b32_e32 v183, 0
	v_mov_b32_e32 v184, 0
	v_mov_b32_e32 v185, 0
	v_mov_b32_e32 v186, 0
	v_mov_b32_e32 v187, 0
	v_mov_b32_e32 v188, 0
	v_mov_b32_e32 v189, 0
	v_mov_b32_e32 v190, 0
	v_mov_b32_e32 v191, 0
	v_mov_b32_e32 v192, 0
	v_mov_b32_e32 v193, 0
	v_mov_b32_e32 v194, 0
	v_mov_b32_e32 v195, 0
	v_mov_b32_e32 v196, 0
	v_mov_b32_e32 v197, 0
	v_exp_f32_e32 v82, v82
	v_exp_f32_e32 v83, v83
	v_exp_f32_e32 v84, v84
	v_exp_f32_e32 v85, v85
	v_cvt_pk_bf16_f32 v142, v82, v83
	v_exp_f32_e32 v86, v86
	v_exp_f32_e32 v87, v87
	v_cvt_pk_bf16_f32 v143, v84, v85
	v_exp_f32_e32 v88, v88
	v_exp_f32_e32 v89, v89
	v_cvt_pk_bf16_f32 v144, v86, v87
	v_exp_f32_e32 v90, v90
	v_exp_f32_e32 v91, v91
	v_cvt_pk_bf16_f32 v145, v88, v89
	v_exp_f32_e32 v92, v92
	v_exp_f32_e32 v93, v93
	v_cvt_pk_bf16_f32 v146, v90, v91
	v_exp_f32_e32 v94, v94
	v_exp_f32_e32 v95, v95
	v_cvt_pk_bf16_f32 v147, v92, v93
	v_exp_f32_e32 v96, v96
	v_exp_f32_e32 v97, v97
	v_cvt_pk_bf16_f32 v148, v94, v95
	v_cvt_pk_bf16_f32 v149, v96, v97
	s_waitcnt vmcnt(0) lgkmcnt(0)
	s_barrier
.Lac_top:
	s_add_i32 s10, s96, 0xfffe0000
	v_mfma_f32_32x32x16_bf16 v[16:31], v[158:161], v[182:185], v[16:31]
	s_mov_b32 m0, s91
	s_nop 0
	buffer_load_dwordx4 v216, s[12:15], s96 offen lds
	ds_read_b128 v[182:185], v225 offset:40960
	v_exp_f32_e32 v98, v98
	v_exp_f32_e32 v99, v99
	v_add_f32_e32 v64, v64, v82
	v_add_f32_e32 v65, v65, v83
	v_mfma_f32_32x32x16_bf16 v[16:31], v[162:165], v[186:189], v[16:31]
	s_mov_b32 m0, s94
	s_nop 0
	buffer_load_dwordx4 v214, s[16:19], s10 offen lds
	ds_read_b128 v[186:189], v226 offset:40960
	v_exp_f32_e32 v100, v100
	v_exp_f32_e32 v101, v101
	v_cvt_pk_bf16_f32 v150, v98, v99
	v_add_f32_e32 v64, v64, v84
	v_add_f32_e32 v65, v65, v85
	v_mfma_f32_32x32x16_bf16 v[16:31], v[166:169], v[190:193], v[16:31]
	s_mov_b32 m0, s95
	s_nop 0
	buffer_load_dwordx4 v215, s[16:19], s10 offen lds
	ds_read_b128 v[190:193], v227 offset:40960
	v_exp_f32_e32 v102, v102
	v_exp_f32_e32 v103, v103
	v_cvt_pk_bf16_f32 v151, v100, v101
	v_add_f32_e32 v64, v64, v86
	v_add_f32_e32 v65, v65, v87
	v_mfma_f32_32x32x16_bf16 v[16:31], v[170:173], v[194:197], v[16:31]
	ds_read_b128 v[194:197], v228 offset:40960
	v_exp_f32_e32 v104, v104
	v_exp_f32_e32 v105, v105
	v_cvt_pk_bf16_f32 v152, v102, v103
	v_add_f32_e32 v64, v64, v88
	v_add_f32_e32 v65, v65, v89
	v_mfma_f32_32x32x16_bf16 v[0:15], v[158:161], v[230:233], v[0:15]
	ds_read_b64_tr_b16 v[246:247], v218 offset:512
	ds_read_b64_tr_b16 v[248:249], v218 offset:2560
	v_exp_f32_e32 v106, v106
	v_exp_f32_e32 v107, v107
	v_cvt_pk_bf16_f32 v153, v104, v105
	v_add_f32_e32 v64, v64, v90
	v_add_f32_e32 v65, v65, v91
	v_mfma_f32_32x32x16_bf16 v[0:15], v[162:165], v[234:237], v[0:15]
	ds_read_b64_tr_b16 v[250:251], v218 offset:4608
	ds_read_b64_tr_b16 v[252:253], v218 offset:6656
	v_exp_f32_e32 v108, v108
	v_exp_f32_e32 v109, v109
	v_cvt_pk_bf16_f32 v154, v106, v107
	v_add_f32_e32 v64, v64, v92
	v_add_f32_e32 v65, v65, v93
	v_mfma_f32_32x32x16_bf16 v[0:15], v[166:169], v[238:241], v[0:15]
	ds_read_b64_tr_b16 v[174:175], v218 offset:8704
	ds_read_b64_tr_b16 v[176:177], v218 offset:10752
	v_exp_f32_e32 v110, v110
	v_exp_f32_e32 v111, v111
	v_cvt_pk_bf16_f32 v155, v108, v109
	v_add_f32_e32 v64, v64, v94
	v_add_f32_e32 v65, v65, v95
	v_mfma_f32_32x32x16_bf16 v[0:15], v[170:173], v[242:245], v[0:15]
	ds_read_b64_tr_b16 v[178:179], v218 offset:12800
	ds_read_b64_tr_b16 v[180:181], v218 offset:14848
	v_exp_f32_e32 v112, v112
	v_exp_f32_e32 v113, v113
	v_cvt_pk_bf16_f32 v156, v110, v111
	v_add_f32_e32 v64, v64, v96
	v_add_f32_e32 v65, v65, v97
	s_add_i32 s96, s96, 0x20000
	s_waitcnt lgkmcnt(11)
	v_mfma_f32_32x32x16_bf16 v[82:97], v[182:185], v[114:117], v[66:81]
	ds_read_b128 v[182:185], v225 offset:45056
	ds_read_b64_tr_b16 v[230:231], v218 offset:0
	ds_read_b64_tr_b16 v[232:233], v218 offset:2048
	v_cvt_pk_bf16_f32 v157, v112, v113
	v_add_f32_e32 v64, v64, v98
	v_add_f32_e32 v65, v65, v99
	v_add_f32_e32 v64, v64, v100
	v_add_f32_e32 v65, v65, v101
	s_waitcnt lgkmcnt(13)
	v_mfma_f32_32x32x16_bf16 v[82:97], v[186:189], v[118:121], v[82:97]
	ds_read_b128 v[186:189], v226 offset:45056
	ds_read_b64_tr_b16 v[234:235], v218 offset:4096
	ds_read_b64_tr_b16 v[236:237], v218 offset:6144
	v_add_f32_e32 v64, v64, v102
	v_add_f32_e32 v65, v65, v103
	v_add_f32_e32 v64, v64, v104
	v_add_f32_e32 v65, v65, v105
	s_waitcnt lgkmcnt(15)
	v_mfma_f32_32x32x16_bf16 v[82:97], v[190:193], v[122:125], v[82:97]
	ds_read_b128 v[190:193], v227 offset:45056
	ds_read_b64_tr_b16 v[238:239], v218 offset:8192
	ds_read_b64_tr_b16 v[240:241], v218 offset:10240
	v_add_f32_e32 v64, v64, v106
	v_add_f32_e32 v65, v65, v107
	v_add_f32_e32 v64, v64, v108
	v_add_f32_e32 v65, v65, v109
	s_waitcnt lgkmcnt(15)
	v_mfma_f32_32x32x16_bf16 v[82:97], v[194:197], v[126:129], v[82:97]
	ds_read_b128 v[194:197], v228 offset:45056
	ds_read_b64_tr_b16 v[242:243], v218 offset:12288
	ds_read_b64_tr_b16 v[244:245], v218 offset:14336
	v_add_f32_e32 v64, v64, v110
	v_add_f32_e32 v65, v65, v111
	v_add_f32_e32 v64, v64, v112
	v_add_f32_e32 v65, v65, v113
	s_waitcnt lgkmcnt(11)
	v_mfma_f32_32x32x16_bf16 v[98:113], v[182:185], v[114:117], v[66:81]
	s_waitcnt lgkmcnt(8)
	v_mfma_f32_32x32x16_bf16 v[98:113], v[186:189], v[118:121], v[98:113]
	s_waitcnt lgkmcnt(5)
	v_mfma_f32_32x32x16_bf16 v[98:113], v[190:193], v[122:125], v[98:113]
	s_waitcnt lgkmcnt(2)
	v_mfma_f32_32x32x16_bf16 v[98:113], v[194:197], v[126:129], v[98:113]
	v_mfma_f32_32x32x16_bf16 v[48:63], v[142:145], v[230:233], v[48:63]
	ds_read_b64_tr_b16 v[182:183], v218 offset:1024
	ds_read_b64_tr_b16 v[184:185], v218 offset:3072
	ds_read_b64_tr_b16 v[186:187], v218 offset:5120
	ds_read_b64_tr_b16 v[188:189], v218 offset:7168
	v_exp_f32_e32 v82, v82
	v_exp_f32_e32 v83, v83
	v_mfma_f32_32x32x16_bf16 v[48:63], v[146:149], v[234:237], v[48:63]
	ds_read_b64_tr_b16 v[190:191], v218 offset:9216
	ds_read_b64_tr_b16 v[192:193], v218 offset:11264
	ds_read_b64_tr_b16 v[194:195], v218 offset:13312
	ds_read_b64_tr_b16 v[196:197], v218 offset:15360
	ds_read_b64_tr_b16 v[230:231], v218 offset:1536
	ds_read_b64_tr_b16 v[232:233], v218 offset:3584
	v_exp_f32_e32 v84, v84
	v_exp_f32_e32 v85, v85
	v_cvt_pk_bf16_f32 v158, v82, v83
	v_mfma_f32_32x32x16_bf16 v[48:63], v[150:153], v[238:241], v[48:63]
	ds_read_b64_tr_b16 v[234:235], v218 offset:5632
	ds_read_b64_tr_b16 v[236:237], v218 offset:7680
	v_exp_f32_e32 v86, v86
	v_exp_f32_e32 v87, v87
	v_cvt_pk_bf16_f32 v159, v84, v85
	s_waitcnt lgkmcnt(12)
	v_mfma_f32_32x32x16_bf16 v[48:63], v[154:157], v[242:245], v[48:63]
	ds_read_b64_tr_b16 v[238:239], v218 offset:9728
	ds_read_b64_tr_b16 v[240:241], v218 offset:11776
	v_exp_f32_e32 v88, v88
	v_exp_f32_e32 v89, v89
	v_cvt_pk_bf16_f32 v160, v86, v87
	v_mfma_f32_32x32x16_bf16 v[32:47], v[142:145], v[246:249], v[32:47]
	ds_read_b64_tr_b16 v[242:243], v218 offset:13824
	ds_read_b64_tr_b16 v[244:245], v218 offset:15872
	v_exp_f32_e32 v90, v90
	v_exp_f32_e32 v91, v91
	v_cvt_pk_bf16_f32 v161, v88, v89
	v_mfma_f32_32x32x16_bf16 v[32:47], v[146:149], v[250:253], v[32:47]
	v_exp_f32_e32 v92, v92
	v_exp_f32_e32 v93, v93
	v_cvt_pk_bf16_f32 v162, v90, v91
	v_mfma_f32_32x32x16_bf16 v[32:47], v[150:153], v[174:177], v[32:47]
	v_exp_f32_e32 v94, v94
	v_exp_f32_e32 v95, v95
	v_cvt_pk_bf16_f32 v163, v92, v93
	v_mfma_f32_32x32x16_bf16 v[32:47], v[154:157], v[178:181], v[32:47]
	v_exp_f32_e32 v96, v96
	v_exp_f32_e32 v97, v97
	v_cvt_pk_bf16_f32 v164, v94, v95
	v_cvt_pk_bf16_f32 v165, v96, v97
	s_waitcnt vmcnt(0) lgkmcnt(0)
	s_barrier
	s_add_i32 s7, s7, 1
	s_add_i32 s10, s7, 1
	s_cmp_ge_u32 s10, s97
	s_cbranch_scc1 .Lac_fin
	s_add_i32 s10, s96, 0xfffe0000
	v_mfma_f32_32x32x16_bf16 v[16:31], v[142:145], v[182:185], v[16:31]
	s_mov_b32 m0, s92
	s_nop 0
	buffer_load_dwordx4 v216, s[12:15], s96 offen lds
	ds_read_b128 v[182:185], v225 offset:32768
	v_exp_f32_e32 v98, v98
	v_exp_f32_e32 v99, v99
	v_add_f32_e32 v64, v64, v82
	v_add_f32_e32 v65, v65, v83
	v_mfma_f32_32x32x16_bf16 v[16:31], v[146:149], v[186:189], v[16:31]
	s_mov_b32 m0, s9
	s_nop 0
	buffer_load_dwordx4 v214, s[16:19], s10 offen lds
	ds_read_b128 v[186:189], v226 offset:32768
	v_exp_f32_e32 v100, v100
	v_exp_f32_e32 v101, v101
	v_cvt_pk_bf16_f32 v166, v98, v99
	v_add_f32_e32 v64, v64, v84
	v_add_f32_e32 v65, v65, v85
	v_mfma_f32_32x32x16_bf16 v[16:31], v[150:153], v[190:193], v[16:31]
	s_mov_b32 m0, s93
	s_nop 0
	buffer_load_dwordx4 v215, s[16:19], s10 offen lds
	ds_read_b128 v[190:193], v227 offset:32768
	v_exp_f32_e32 v102, v102
	v_exp_f32_e32 v103, v103
	v_cvt_pk_bf16_f32 v167, v100, v101
	v_add_f32_e32 v64, v64, v86
	v_add_f32_e32 v65, v65, v87
	v_mfma_f32_32x32x16_bf16 v[16:31], v[154:157], v[194:197], v[16:31]
	ds_read_b128 v[194:197], v228 offset:32768
	v_exp_f32_e32 v104, v104
	v_exp_f32_e32 v105, v105
	v_cvt_pk_bf16_f32 v168, v102, v103
	v_add_f32_e32 v64, v64, v88
	v_add_f32_e32 v65, v65, v89
	v_mfma_f32_32x32x16_bf16 v[0:15], v[142:145], v[230:233], v[0:15]
	ds_read_b64_tr_b16 v[246:247], v218 offset:16896
	ds_read_b64_tr_b16 v[248:249], v218 offset:18944
	v_exp_f32_e32 v106, v106
	v_exp_f32_e32 v107, v107
	v_cvt_pk_bf16_f32 v169, v104, v105
	v_add_f32_e32 v64, v64, v90
	v_add_f32_e32 v65, v65, v91
	v_mfma_f32_32x32x16_bf16 v[0:15], v[146:149], v[234:237], v[0:15]
	ds_read_b64_tr_b16 v[250:251], v218 offset:20992
	ds_read_b64_tr_b16 v[252:253], v218 offset:23040
	v_exp_f32_e32 v108, v108
	v_exp_f32_e32 v109, v109
	v_cvt_pk_bf16_f32 v170, v106, v107
	v_add_f32_e32 v64, v64, v92
	v_add_f32_e32 v65, v65, v93
	v_mfma_f32_32x32x16_bf16 v[0:15], v[150:153], v[238:241], v[0:15]
	ds_read_b64_tr_b16 v[174:175], v218 offset:25088
	ds_read_b64_tr_b16 v[176:177], v218 offset:27136
	v_exp_f32_e32 v110, v110
	v_exp_f32_e32 v111, v111
	v_cvt_pk_bf16_f32 v171, v108, v109
	v_add_f32_e32 v64, v64, v94
	v_add_f32_e32 v65, v65, v95
	v_mfma_f32_32x32x16_bf16 v[0:15], v[154:157], v[242:245], v[0:15]
	ds_read_b64_tr_b16 v[178:179], v218 offset:29184
	ds_read_b64_tr_b16 v[180:181], v218 offset:31232
	v_exp_f32_e32 v112, v112
	v_exp_f32_e32 v113, v113
	v_cvt_pk_bf16_f32 v172, v110, v111
	v_add_f32_e32 v64, v64, v96
	v_add_f32_e32 v65, v65, v97
	s_add_i32 s96, s96, 0x20000
	s_waitcnt lgkmcnt(11)
	v_mfma_f32_32x32x16_bf16 v[82:97], v[182:185], v[114:117], v[66:81]
	ds_read_b128 v[182:185], v225 offset:36864
	ds_read_b64_tr_b16 v[230:231], v218 offset:16384
	ds_read_b64_tr_b16 v[232:233], v218 offset:18432
	v_cvt_pk_bf16_f32 v173, v112, v113
	v_add_f32_e32 v64, v64, v98
	v_add_f32_e32 v65, v65, v99
	v_add_f32_e32 v64, v64, v100
	v_add_f32_e32 v65, v65, v101
	s_waitcnt lgkmcnt(13)
	v_mfma_f32_32x32x16_bf16 v[82:97], v[186:189], v[118:121], v[82:97]
	ds_read_b128 v[186:189], v226 offset:36864
	ds_read_b64_tr_b16 v[234:235], v218 offset:20480
	ds_read_b64_tr_b16 v[236:237], v218 offset:22528
	v_add_f32_e32 v64, v64, v102
	v_add_f32_e32 v65, v65, v103
	v_add_f32_e32 v64, v64, v104
	v_add_f32_e32 v65, v65, v105
	s_waitcnt lgkmcnt(15)
	v_mfma_f32_32x32x16_bf16 v[82:97], v[190:193], v[122:125], v[82:97]
	ds_read_b128 v[190:193], v227 offset:36864
	ds_read_b64_tr_b16 v[238:239], v218 offset:24576
	ds_read_b64_tr_b16 v[240:241], v218 offset:26624
	v_add_f32_e32 v64, v64, v106
	v_add_f32_e32 v65, v65, v107
	v_add_f32_e32 v64, v64, v108
	v_add_f32_e32 v65, v65, v109
	s_waitcnt lgkmcnt(15)
	v_mfma_f32_32x32x16_bf16 v[82:97], v[194:197], v[126:129], v[82:97]
	ds_read_b128 v[194:197], v228 offset:36864
	ds_read_b64_tr_b16 v[242:243], v218 offset:28672
	ds_read_b64_tr_b16 v[244:245], v218 offset:30720
	v_add_f32_e32 v64, v64, v110
	v_add_f32_e32 v65, v65, v111
	v_add_f32_e32 v64, v64, v112
	v_add_f32_e32 v65, v65, v113
	s_waitcnt lgkmcnt(11)
	v_mfma_f32_32x32x16_bf16 v[98:113], v[182:185], v[114:117], v[66:81]
	s_waitcnt lgkmcnt(8)
	v_mfma_f32_32x32x16_bf16 v[98:113], v[186:189], v[118:121], v[98:113]
	s_waitcnt lgkmcnt(5)
	v_mfma_f32_32x32x16_bf16 v[98:113], v[190:193], v[122:125], v[98:113]
	s_waitcnt lgkmcnt(2)
	v_mfma_f32_32x32x16_bf16 v[98:113], v[194:197], v[126:129], v[98:113]
	v_mfma_f32_32x32x16_bf16 v[48:63], v[158:161], v[230:233], v[48:63]
	ds_read_b64_tr_b16 v[182:183], v218 offset:17408
	ds_read_b64_tr_b16 v[184:185], v218 offset:19456
	ds_read_b64_tr_b16 v[186:187], v218 offset:21504
	ds_read_b64_tr_b16 v[188:189], v218 offset:23552
	v_exp_f32_e32 v82, v82
	v_exp_f32_e32 v83, v83
	v_mfma_f32_32x32x16_bf16 v[48:63], v[162:165], v[234:237], v[48:63]
	ds_read_b64_tr_b16 v[190:191], v218 offset:25600
	ds_read_b64_tr_b16 v[192:193], v218 offset:27648
	ds_read_b64_tr_b16 v[194:195], v218 offset:29696
	ds_read_b64_tr_b16 v[196:197], v218 offset:31744
	ds_read_b64_tr_b16 v[230:231], v218 offset:17920
	ds_read_b64_tr_b16 v[232:233], v218 offset:19968
	v_exp_f32_e32 v84, v84
	v_exp_f32_e32 v85, v85
	v_cvt_pk_bf16_f32 v142, v82, v83
	v_mfma_f32_32x32x16_bf16 v[48:63], v[166:169], v[238:241], v[48:63]
	ds_read_b64_tr_b16 v[234:235], v218 offset:22016
	ds_read_b64_tr_b16 v[236:237], v218 offset:24064
	v_exp_f32_e32 v86, v86
	v_exp_f32_e32 v87, v87
	v_cvt_pk_bf16_f32 v143, v84, v85
	s_waitcnt lgkmcnt(12)
	v_mfma_f32_32x32x16_bf16 v[48:63], v[170:173], v[242:245], v[48:63]
	ds_read_b64_tr_b16 v[238:239], v218 offset:26112
	ds_read_b64_tr_b16 v[240:241], v218 offset:28160
	v_exp_f32_e32 v88, v88
	v_exp_f32_e32 v89, v89
	v_cvt_pk_bf16_f32 v144, v86, v87
	v_mfma_f32_32x32x16_bf16 v[32:47], v[158:161], v[246:249], v[32:47]
	ds_read_b64_tr_b16 v[242:243], v218 offset:30208
	ds_read_b64_tr_b16 v[244:245], v218 offset:32256
	v_exp_f32_e32 v90, v90
	v_exp_f32_e32 v91, v91
	v_cvt_pk_bf16_f32 v145, v88, v89
	v_mfma_f32_32x32x16_bf16 v[32:47], v[162:165], v[250:253], v[32:47]
	v_exp_f32_e32 v92, v92
	v_exp_f32_e32 v93, v93
	v_cvt_pk_bf16_f32 v146, v90, v91
	v_mfma_f32_32x32x16_bf16 v[32:47], v[166:169], v[174:177], v[32:47]
	v_exp_f32_e32 v94, v94
	v_exp_f32_e32 v95, v95
	v_cvt_pk_bf16_f32 v147, v92, v93
	v_mfma_f32_32x32x16_bf16 v[32:47], v[170:173], v[178:181], v[32:47]
	v_exp_f32_e32 v96, v96
	v_exp_f32_e32 v97, v97
	v_cvt_pk_bf16_f32 v148, v94, v95
	v_cvt_pk_bf16_f32 v149, v96, v97
	s_waitcnt vmcnt(0) lgkmcnt(0)
	s_barrier
	s_add_i32 s7, s7, 1
	s_branch .Lac_top
.Lac_fin:
	s_add_i32 s10, s96, 0xfffe0000
	s_cmpk_lt_u32 s97, 0x100
	s_cselect_b32 s11, 1, 0
	v_mfma_f32_32x32x16_bf16 v[16:31], v[142:145], v[182:185], v[16:31]
	s_cmp_eq_u32 s11, 0
	s_cbranch_scc1 .Lac_fin_nodma
	s_mov_b32 m0, s9
	s_nop 0
	buffer_load_dwordx4 v214, s[16:19], s10 offen lds
	s_mov_b32 m0, s93
	s_nop 0
	buffer_load_dwordx4 v215, s[16:19], s10 offen lds
.Lac_fin_nodma:
	v_exp_f32_e32 v98, v98
	v_exp_f32_e32 v99, v99
	v_add_f32_e32 v64, v64, v82
	v_add_f32_e32 v65, v65, v83
	v_mfma_f32_32x32x16_bf16 v[16:31], v[146:149], v[186:189], v[16:31]
	v_exp_f32_e32 v100, v100
	v_exp_f32_e32 v101, v101
	v_cvt_pk_bf16_f32 v166, v98, v99
	v_add_f32_e32 v64, v64, v84
	v_add_f32_e32 v65, v65, v85
	v_mfma_f32_32x32x16_bf16 v[16:31], v[150:153], v[190:193], v[16:31]
	v_exp_f32_e32 v102, v102
	v_exp_f32_e32 v103, v103
	v_cvt_pk_bf16_f32 v167, v100, v101
	v_add_f32_e32 v64, v64, v86
	v_add_f32_e32 v65, v65, v87
	v_mfma_f32_32x32x16_bf16 v[16:31], v[154:157], v[194:197], v[16:31]
	v_exp_f32_e32 v104, v104
	v_exp_f32_e32 v105, v105
	v_cvt_pk_bf16_f32 v168, v102, v103
	v_add_f32_e32 v64, v64, v88
	v_add_f32_e32 v65, v65, v89
	v_mfma_f32_32x32x16_bf16 v[0:15], v[142:145], v[230:233], v[0:15]
	ds_read_b64_tr_b16 v[246:247], v218 offset:16896
	ds_read_b64_tr_b16 v[248:249], v218 offset:18944
	v_exp_f32_e32 v106, v106
	v_exp_f32_e32 v107, v107
	v_cvt_pk_bf16_f32 v169, v104, v105
	v_add_f32_e32 v64, v64, v90
	v_add_f32_e32 v65, v65, v91
	v_mfma_f32_32x32x16_bf16 v[0:15], v[146:149], v[234:237], v[0:15]
	ds_read_b64_tr_b16 v[250:251], v218 offset:20992
	ds_read_b64_tr_b16 v[252:253], v218 offset:23040
	v_exp_f32_e32 v108, v108
	v_exp_f32_e32 v109, v109
	v_cvt_pk_bf16_f32 v170, v106, v107
	v_add_f32_e32 v64, v64, v92
	v_add_f32_e32 v65, v65, v93
	v_mfma_f32_32x32x16_bf16 v[0:15], v[150:153], v[238:241], v[0:15]
	ds_read_b64_tr_b16 v[174:175], v218 offset:25088
	ds_read_b64_tr_b16 v[176:177], v218 offset:27136
	v_exp_f32_e32 v110, v110
	v_exp_f32_e32 v111, v111
	v_cvt_pk_bf16_f32 v171, v108, v109
	v_add_f32_e32 v64, v64, v94
	v_add_f32_e32 v65, v65, v95
	v_mfma_f32_32x32x16_bf16 v[0:15], v[154:157], v[242:245], v[0:15]
	ds_read_b64_tr_b16 v[178:179], v218 offset:29184
	ds_read_b64_tr_b16 v[180:181], v218 offset:31232
	v_exp_f32_e32 v112, v112
	v_exp_f32_e32 v113, v113
	v_cvt_pk_bf16_f32 v172, v110, v111
	v_add_f32_e32 v64, v64, v96
	v_add_f32_e32 v65, v65, v97
	s_add_i32 s96, s96, 0x20000
	ds_read_b64_tr_b16 v[230:231], v218 offset:16384
	ds_read_b64_tr_b16 v[232:233], v218 offset:18432
	v_cvt_pk_bf16_f32 v173, v112, v113
	v_add_f32_e32 v64, v64, v98
	v_add_f32_e32 v65, v65, v99
	v_add_f32_e32 v64, v64, v100
	v_add_f32_e32 v65, v65, v101
	ds_read_b64_tr_b16 v[234:235], v218 offset:20480
	ds_read_b64_tr_b16 v[236:237], v218 offset:22528
	v_add_f32_e32 v64, v64, v102
	v_add_f32_e32 v65, v65, v103
	v_add_f32_e32 v64, v64, v104
	v_add_f32_e32 v65, v65, v105
	ds_read_b64_tr_b16 v[238:239], v218 offset:24576
	ds_read_b64_tr_b16 v[240:241], v218 offset:26624
	v_add_f32_e32 v64, v64, v106
	v_add_f32_e32 v65, v65, v107
	v_add_f32_e32 v64, v64, v108
	v_add_f32_e32 v65, v65, v109
	ds_read_b64_tr_b16 v[242:243], v218 offset:28672
	ds_read_b64_tr_b16 v[244:245], v218 offset:30720
	v_add_f32_e32 v64, v64, v110
	v_add_f32_e32 v65, v65, v111
	v_add_f32_e32 v64, v64, v112
	v_add_f32_e32 v65, v65, v113
	s_waitcnt lgkmcnt(6)
	v_mfma_f32_32x32x16_bf16 v[48:63], v[158:161], v[230:233], v[48:63]
	ds_read_b64_tr_b16 v[182:183], v218 offset:17408
	ds_read_b64_tr_b16 v[184:185], v218 offset:19456
	ds_read_b64_tr_b16 v[186:187], v218 offset:21504
	ds_read_b64_tr_b16 v[188:189], v218 offset:23552
	s_waitcnt lgkmcnt(8)
	v_mfma_f32_32x32x16_bf16 v[48:63], v[162:165], v[234:237], v[48:63]
	ds_read_b64_tr_b16 v[190:191], v218 offset:25600
	ds_read_b64_tr_b16 v[192:193], v218 offset:27648
	ds_read_b64_tr_b16 v[194:195], v218 offset:29696
	ds_read_b64_tr_b16 v[196:197], v218 offset:31744
	ds_read_b64_tr_b16 v[230:231], v218 offset:17920
	ds_read_b64_tr_b16 v[232:233], v218 offset:19968
	s_waitcnt lgkmcnt(12)
	v_mfma_f32_32x32x16_bf16 v[48:63], v[166:169], v[238:241], v[48:63]
	ds_read_b64_tr_b16 v[234:235], v218 offset:22016
	ds_read_b64_tr_b16 v[236:237], v218 offset:24064
	s_waitcnt lgkmcnt(12)
	v_mfma_f32_32x32x16_bf16 v[48:63], v[170:173], v[242:245], v[48:63]
	ds_read_b64_tr_b16 v[238:239], v218 offset:26112
	ds_read_b64_tr_b16 v[240:241], v218 offset:28160
	v_mfma_f32_32x32x16_bf16 v[32:47], v[158:161], v[246:249], v[32:47]
	ds_read_b64_tr_b16 v[242:243], v218 offset:30208
	ds_read_b64_tr_b16 v[244:245], v218 offset:32256
	v_mfma_f32_32x32x16_bf16 v[32:47], v[162:165], v[250:253], v[32:47]
	v_mfma_f32_32x32x16_bf16 v[32:47], v[166:169], v[174:177], v[32:47]
	v_mfma_f32_32x32x16_bf16 v[32:47], v[170:173], v[178:181], v[32:47]
	s_waitcnt lgkmcnt(14)
	v_mfma_f32_32x32x16_bf16 v[16:31], v[158:161], v[182:185], v[16:31]
	s_waitcnt lgkmcnt(12)
	v_mfma_f32_32x32x16_bf16 v[16:31], v[162:165], v[186:189], v[16:31]
	s_waitcnt lgkmcnt(10)
	v_mfma_f32_32x32x16_bf16 v[16:31], v[166:169], v[190:193], v[16:31]
	s_waitcnt lgkmcnt(8)
	v_mfma_f32_32x32x16_bf16 v[16:31], v[170:173], v[194:197], v[16:31]
	s_waitcnt lgkmcnt(6)
	v_mfma_f32_32x32x16_bf16 v[0:15], v[158:161], v[230:233], v[0:15]
	s_waitcnt lgkmcnt(4)
	v_mfma_f32_32x32x16_bf16 v[0:15], v[162:165], v[234:237], v[0:15]
	s_waitcnt lgkmcnt(2)
	v_mfma_f32_32x32x16_bf16 v[0:15], v[166:169], v[238:241], v[0:15]
	s_waitcnt lgkmcnt(0)
	v_mfma_f32_32x32x16_bf16 v[0:15], v[170:173], v[242:245], v[0:15]
	v_add_f32_e32 v64, v64, v65
	s_waitcnt vmcnt(0) lgkmcnt(0)
	s_barrier
	s_add_i32 s7, s7, 1
	s_cmp_eq_u32 s98, 0
	s_cbranch_scc1 .LBB0_463

	.amdhsa_kernel _Z8fwd_mega4Args
		.amdhsa_group_segment_fixed_size 0
		.amdhsa_private_segment_fixed_size 0
		.amdhsa_kernarg_size 432
		.amdhsa_user_sgpr_count 2
		.amdhsa_user_sgpr_dispatch_ptr 0
		.amdhsa_user_sgpr_queue_ptr 0
		.amdhsa_user_sgpr_kernarg_segment_ptr 1
		.amdhsa_user_sgpr_dispatch_id 0
		.amdhsa_user_sgpr_kernarg_preload_length 0
		.amdhsa_user_sgpr_kernarg_preload_offset 0
		.amdhsa_user_sgpr_private_segment_size 0
		.amdhsa_uses_dynamic_stack 0
		.amdhsa_enable_private_segment 0
		.amdhsa_system_sgpr_workgroup_id_x 1
		.amdhsa_system_sgpr_workgroup_id_y 0
		.amdhsa_system_sgpr_workgroup_id_z 0
		.amdhsa_system_sgpr_workgroup_info 0
		.amdhsa_system_vgpr_workitem_id 2
		.amdhsa_next_free_vgpr 256
		.amdhsa_next_free_sgpr 99
		.amdhsa_accum_offset 256
		.amdhsa_reserve_vcc 1
		.amdhsa_float_round_mode_32 0
		.amdhsa_float_round_mode_16_64 0
		.amdhsa_float_denorm_mode_32 3
		.amdhsa_float_denorm_mode_16_64 3
		.amdhsa_dx10_clamp 1
		.amdhsa_ieee_mode 1
		.amdhsa_fp16_overflow 0
		.amdhsa_tg_split 0
		.amdhsa_exception_fp_ieee_invalid_op 0
		.amdhsa_exception_fp_denorm_src 0
		.amdhsa_exception_fp_ieee_div_zero 0
		.amdhsa_exception_fp_ieee_overflow 0
		.amdhsa_exception_fp_ieee_underflow 0
		.amdhsa_exception_fp_ieee_inexact 0
		.amdhsa_exception_int_div_zero 0
	.end_amdhsa_kernel

amdhsa.kernels:
  - .agpr_count:     0
    .args:
      - .offset:         0
        .size:           176
        .value_kind:     by_value
      - .offset:         176
        .size:           4
        .value_kind:     hidden_block_count_x
      - .offset:         180
        .size:           4
        .value_kind:     hidden_block_count_y
      - .offset:         184
        .size:           4
        .value_kind:     hidden_block_count_z
      - .offset:         188
        .size:           2
        .value_kind:     hidden_group_size_x
      - .offset:         190
        .size:           2
        .value_kind:     hidden_group_size_y
      - .offset:         192
        .size:           2
        .value_kind:     hidden_group_size_z
      - .offset:         194
        .size:           2
        .value_kind:     hidden_remainder_x
      - .offset:         196
        .size:           2
        .value_kind:     hidden_remainder_y
      - .offset:         198
        .size:           2
        .value_kind:     hidden_remainder_z
      - .offset:         216
        .size:           8
        .value_kind:     hidden_global_offset_x
      - .offset:         224
        .size:           8
        .value_kind:     hidden_global_offset_y
      - .offset:         232
        .size:           8
        .value_kind:     hidden_global_offset_z
      - .offset:         240
        .size:           2
        .value_kind:     hidden_grid_dims
      - .offset:         264
        .size:           8
        .value_kind:     hidden_multigrid_sync_arg
      - .offset:         296
        .size:           4
        .value_kind:     hidden_dynamic_lds_size
    .group_segment_fixed_size: 0
    .kernarg_segment_align: 8
    .kernarg_segment_size: 432
    .language:       OpenCL C
    .language_version:
      - 2
      - 0
    .max_flat_workgroup_size: 512
    .name:           _Z8fwd_mega4Args
    .private_segment_fixed_size: 0
    .sgpr_count:     105
    .sgpr_spill_count: 12
    .symbol:         _Z8fwd_mega4Args.kd
    .uniform_work_group_size: 1
    .uses_dynamic_stack: false
    .vgpr_count:     256
    .vgpr_spill_count: 0
    .wavefront_size: 64
